# P15 seam: first row-panel poll issued together with the XCD arrival atomic
# baseline (speedup 1.0000x reference)
.LBB0_1781:
	s_waitcnt vmcnt(0)
	s_waitcnt vmcnt(0) lgkmcnt(0)
	s_barrier
	s_and_saveexec_b64 s[8:9], s[92:93]
	s_cbranch_execz .LBB0_1833
	s_and_b32 s0, s2, 7
	s_lshl_b32 s0, s0, 3
	s_lshr_b32 s1, s2, 5
	s_add_i32 s1, s0, s1
	s_lshl_b32 s1, s1, 8
	s_add_i32 s1, s1, 0x2b5d028
	v_mov_b32_e32 v2, s1
	v_mov_b32_e32 v3, 1
	global_atomic_add v2, v3, s[88:89]
	v_mov_b32_e32 v2, 0x22000
	ds_read_b32 v4, v2
	s_lshl_b32 s1, s87, 8
	s_add_i32 s1, s1, 0x2b5d02c
	v_mov_b32_e32 v2, s1
	global_atomic_add v6, v2, v3, s[88:89] sc0
	s_lshr_b32 s1, s2, 3
	s_and_b32 s1, s1, 7
	s_add_i32 s1, s0, s1
	s_lshl_b32 s1, s1, 8
	s_add_i32 s1, s1, 0x2b5d028
	v_mov_b32_e32 v7, s1
	global_load_dword v8, v7, s[88:89] sc1
	s_waitcnt vmcnt(0) lgkmcnt(0)
	v_add_u32_e32 v6, 1, v6
	v_cmp_eq_u32_e32 vcc, v6, v4
	s_cbranch_vccz .Lp15_notlast
	buffer_wbl2 sc1
	s_waitcnt vmcnt(0)
	v_mov_b32_e32 v2, 0x2b5d030
	global_atomic_add v2, v3, s[88:89]
.Lp15_notlast:
	s_lshr_b32 s1, s2, 3
	s_and_b32 s1, s1, 7
	s_add_i32 s1, s0, s1
	s_lshl_b32 s1, s1, 8
	s_add_i32 s1, s1, 0x2b5d028
	v_mov_b32_e32 v2, s1
	s_mov_b32 s1, 0x100000
	v_cmp_lt_u32_e32 vcc, 3, v8
	s_cbranch_vccnz .Lp15_pdone
